# phase 0 rmsnorm: paired row-sum ds_bpermute butterflies replaced by permlane swaps and DPP row rotations
# baseline (speedup 1.0000x reference)
; template <int NR>
; DI void rms_rows(const float* __restrict__ xr, const float* __restrict__ g, u16* __restrict__ dst, int lane) {
;   float4 v[NR][4];
; #pragma unroll
;   for (int r = 0; r < NR; ++r)
; #pragma unroll
;     for (int i = 0; i < 4; ++i) v[r][i] = *(const float4*)(xr + (size_t)r * 1024 + lane * 4 + 256 * i);
;   float4 gg[4];
; #pragma unroll
;   for (int i = 0; i < 4; ++i) gg[i] = *(const float4*)(g + lane * 4 + 256 * i);
; #pragma unroll
;   for (int r = 0; r < NR; ++r) {
;     float ss = 0.f;
; #pragma unroll
;     for (int i = 0; i < 4; ++i) ss += v[r][i].x * v[r][i].x + v[r][i].y * v[r][i].y + v[r][i].z * v[r][i].z + v[r][i].w * v[r][i].w;
;     ss = wave_sum(ss);
;     const float rr = rsqrtf(ss * (1.f / 1024.f) + 1e-6f);
; DI void phase_prep(const Params& p, char* smem, int part, int vb) {
;     ...
;       if (it < 1024) {
;         int row = it * 16 + wave * 4;
;         rms_rows<4>(p.x + (size_t)row * 1024, p.g_mix, (u16*)(ws + WS_XN) + (size_t)row * 1024, lane);
;         continue;
.LBB0_78:
	v_lshl_add_u32 v68, s7, 4, v70
	v_ashrrev_i32_e32 v69, 31, v68
	v_lshlrev_b64 v[0:1], 12, v[68:69]
	v_lshl_add_u64 v[32:33], v[64:65], 0, v[0:1]
	v_add_co_u32_e32 v0, vcc, s23, v32
	global_load_dwordx4 v[16:19], v[32:33], off
	global_load_dwordx4 v[20:23], v[32:33], off offset:1024
	global_load_dwordx4 v[24:27], v[32:33], off offset:2048
	global_load_dwordx4 v[28:31], v[32:33], off offset:3072
	v_addc_co_u32_e32 v1, vcc, 0, v33, vcc
	v_add_co_u32_e32 v56, vcc, s25, v32
	v_and_b32_e32 v34, 64, v72
	s_nop 0
	v_addc_co_u32_e32 v57, vcc, 0, v33, vcc
	global_load_dwordx4 v[12:15], v[56:57], off offset:-4096
	global_load_dwordx4 v[8:11], v[0:1], off offset:1024
	global_load_dwordx4 v[4:7], v[0:1], off offset:2048
	s_nop 0
	global_load_dwordx4 v[0:3], v[0:1], off offset:3072
	v_xor_b32_e32 v35, 32, v72
	v_add_u32_e32 v94, 64, v34
	v_cmp_lt_i32_e32 vcc, v35, v94
	v_xor_b32_e32 v60, 16, v72
	v_xor_b32_e32 v73, 8, v72
	v_cndmask_b32_e32 v34, v72, v35, vcc
	v_lshlrev_b32_e32 v98, 2, v34
	v_add_co_u32_e32 v58, vcc, s26, v32
	global_load_dwordx4 v[36:39], v[66:67], off
	s_nop 0
	v_addc_co_u32_e32 v59, vcc, 0, v33, vcc
	v_cmp_lt_i32_e32 vcc, v60, v94
	global_load_dwordx4 v[32:35], v[58:59], off offset:3072
	global_load_dwordx4 v[40:43], v[58:59], off
	s_waitcnt vmcnt(10)
	v_mov_b32_e32 v48, v17
	s_waitcnt vmcnt(9)
	v_mov_b32_e32 v49, v21
	s_waitcnt vmcnt(8)
	v_mov_b32_e32 v54, v25
	s_waitcnt vmcnt(7)
	v_mov_b32_e32 v55, v29
	v_mov_b32_e32 v46, v16
	v_mov_b32_e32 v47, v20
	v_mov_b32_e32 v52, v24
	v_mov_b32_e32 v53, v28
	v_pk_mul_f32 v[48:49], v[48:49], v[48:49]
	v_pk_mul_f32 v[54:55], v[54:55], v[54:55]
	s_waitcnt vmcnt(6)
	v_mov_b32_e32 v80, v13
	s_waitcnt vmcnt(5)
	v_mov_b32_e32 v81, v9
	v_mov_b32_e32 v44, v18
	v_mov_b32_e32 v45, v22
	v_mov_b32_e32 v50, v26
	v_mov_b32_e32 v51, v30
	v_mov_b32_e32 v78, v12
	v_mov_b32_e32 v79, v8
	s_waitcnt vmcnt(4)
	v_mov_b32_e32 v84, v5
	s_waitcnt vmcnt(3)
	v_mov_b32_e32 v85, v1
	v_pk_fma_f32 v[46:47], v[46:47], v[46:47], v[48:49]
	v_pk_fma_f32 v[48:49], v[52:53], v[52:53], v[54:55]
	v_pk_mul_f32 v[52:53], v[80:81], v[80:81]
	v_mov_b32_e32 v82, v4
	v_mov_b32_e32 v83, v0
	v_mov_b32_e32 v86, v14
	v_mov_b32_e32 v87, v10
	v_pk_mul_f32 v[54:55], v[84:85], v[84:85]
	v_pk_fma_f32 v[44:45], v[44:45], v[44:45], v[46:47]
	v_pk_fma_f32 v[46:47], v[50:51], v[50:51], v[48:49]
	v_pk_fma_f32 v[48:49], v[78:79], v[78:79], v[52:53]
	v_mov_b32_e32 v74, v19
	v_mov_b32_e32 v75, v23
	v_mov_b32_e32 v88, v6
	v_mov_b32_e32 v89, v2
	v_mov_b32_e32 v90, v15
	v_mov_b32_e32 v91, v11
	v_pk_fma_f32 v[50:51], v[82:83], v[82:83], v[54:55]
	v_pk_fma_f32 v[48:49], v[86:87], v[86:87], v[48:49]
	v_mov_b32_e32 v76, v27
	v_mov_b32_e32 v77, v31
	v_mov_b32_e32 v92, v7
	v_mov_b32_e32 v93, v3
	v_pk_fma_f32 v[44:45], v[74:75], v[74:75], v[44:45]
	v_pk_fma_f32 v[50:51], v[88:89], v[88:89], v[50:51]
	v_pk_fma_f32 v[48:49], v[90:91], v[90:91], v[48:49]
	v_pk_fma_f32 v[46:47], v[76:77], v[76:77], v[46:47]
	v_pk_fma_f32 v[50:51], v[92:93], v[92:93], v[50:51]
	v_mov_b32_e32 v53, v44
	v_mov_b32_e32 v52, v48
	v_mov_b32_e32 v44, v49
	v_mov_b32_e32 v55, v46
	v_mov_b32_e32 v54, v50
	v_pk_add_f32 v[44:45], v[52:53], v[44:45]
	v_mov_b32_e32 v46, v51
	v_pk_add_f32 v[44:45], v[44:45], v[54:55]
	v_cndmask_b32_e32 v52, v72, v60, vcc
	v_pk_add_f32 v[48:49], v[44:45], v[46:47]
	v_mov_b32_e32 v51, v49
	s_nop 1
	v_permlane32_swap_b32_e32 v51, v49
	s_nop 1
	v_mov_b32_e32 v50, v48
	s_nop 1
	v_permlane32_swap_b32_e32 v50, v48
	s_nop 1
	v_lshlrev_b32_e32 v99, 2, v52
	v_cmp_lt_i32_e32 vcc, v73, v94
	global_load_dwordx4 v[44:47], v[66:67], off offset:1024
	global_load_dwordx4 v[52:55], v[66:67], off offset:2048
	s_waitcnt lgkmcnt(0)
	v_pk_add_f32 v[48:49], v[48:49], v[50:51]
	v_mov_b32_e32 v51, v49
	s_nop 1
	v_permlane16_swap_b32_e32 v51, v49
	s_nop 1
	v_mov_b32_e32 v50, v48
	s_nop 1
	v_permlane16_swap_b32_e32 v50, v48
	s_nop 1
	v_cndmask_b32_e32 v60, v72, v73, vcc
	v_lshlrev_b32_e32 v73, 2, v60
	v_xor_b32_e32 v60, 4, v72
	v_cmp_lt_i32_e32 vcc, v60, v94
	s_waitcnt lgkmcnt(0)
	v_pk_add_f32 v[74:75], v[48:49], v[50:51]
	s_nop 1
	v_mov_b32_dpp v77, v75 row_ror:8 row_mask:0xf bank_mask:0xf
	s_nop 0
	s_nop 1
	v_mov_b32_dpp v76, v74 row_ror:8 row_mask:0xf bank_mask:0xf
	s_nop 0
	v_cndmask_b32_e32 v60, v72, v60, vcc
	v_lshlrev_b32_e32 v100, 2, v60
	v_xor_b32_e32 v60, 2, v72
	global_load_dwordx4 v[48:51], v[66:67], off offset:3072
	s_waitcnt lgkmcnt(0)
	v_pk_add_f32 v[82:83], v[74:75], v[76:77]
	s_nop 1
	v_mov_b32_dpp v85, v83 row_ror:4 row_mask:0xf bank_mask:0xf
	s_nop 0
	s_nop 1
	v_mov_b32_dpp v84, v82 row_ror:4 row_mask:0xf bank_mask:0xf
	s_nop 0
	v_cmp_lt_i32_e32 vcc, v60, v94
	global_load_dwordx4 v[74:77], v[56:57], off
	global_load_dwordx4 v[78:81], v[56:57], off offset:1024
	v_cndmask_b32_e32 v60, v72, v60, vcc
	v_lshlrev_b32_e32 v101, 2, v60
	s_waitcnt lgkmcnt(0)
	v_pk_add_f32 v[90:91], v[82:83], v[84:85]
	s_nop 1
	v_mov_b32_dpp v93, v91 row_ror:2 row_mask:0xf bank_mask:0xf
	s_nop 0
	s_nop 1
	v_mov_b32_dpp v92, v90 row_ror:2 row_mask:0xf bank_mask:0xf
	s_nop 0
	v_xor_b32_e32 v60, 1, v72
	v_cmp_lt_i32_e32 vcc, v60, v94
	global_load_dwordx4 v[82:85], v[56:57], off offset:2048
	global_load_dwordx4 v[86:89], v[56:57], off offset:3072
	v_cndmask_b32_e32 v60, v72, v60, vcc
	s_waitcnt lgkmcnt(0)
	v_pk_add_f32 v[56:57], v[90:91], v[92:93]
	v_lshlrev_b32_e32 v102, 2, v60
	s_nop 1
	v_mov_b32_dpp v95, v57 row_ror:1 row_mask:0xf bank_mask:0xf
	s_nop 0
	s_nop 1
	v_mov_b32_dpp v94, v56 row_ror:1 row_mask:0xf bank_mask:0xf
	s_nop 0
	global_load_dwordx4 v[90:93], v[58:59], off offset:1024
	s_waitcnt lgkmcnt(0)
; template <int NR>
; DI void rms_rows(const float* __restrict__ xr, const float* __restrict__ g, u16* __restrict__ dst, int lane) {
;     ...
;     for (int i = 0; i < 4; ++i) ss += v[r][i].x * v[r][i].x + v[r][i].y * v[r][i].y + v[r][i].z * v[r][i].z + v[r][i].w * v[r][i].w;
;     ss = wave_sum(ss);
;     const float rr = rsqrtf(ss * (1.f / 1024.f) + 1e-6f);
; #pragma unroll
;     for (int i = 0; i < 4; ++i) {
;       uint2 o;
;       o.x = pack2(v[r][i].x * rr * gg[i].x, v[r][i].y * rr * gg[i].y);
;       o.y = pack2(v[r][i].z * rr * gg[i].z, v[r][i].w * rr * gg[i].w);
;       *(uint2*)(dst + (size_t)r * 1024 + lane * 4 + 256 * i) = o;
	v_pk_add_f32 v[56:57], v[56:57], v[94:95]
	v_mov_b64_e32 v[94:95], s[14:15]
	v_pk_fma_f32 v[96:97], v[56:57], s[6:7], v[94:95] op_sel_hi:[1,0,0]
	s_nop 0
	v_mul_f32_e32 v56, 0x4b800000, v97
	v_cmp_gt_f32_e32 vcc, s24, v97
	s_nop 1
	v_cndmask_b32_e32 v60, v97, v56, vcc
	global_load_dwordx4 v[56:59], v[58:59], off offset:2048
	v_rsq_f32_e32 v60, v60
	s_nop 0
	v_mul_f32_e32 v97, 0x45800000, v60
	v_cndmask_b32_e32 v60, v60, v97, vcc
	v_pk_mul_f32 v[16:17], v[16:17], v[60:61] op_sel_hi:[1,0]
	v_pk_mul_f32 v[18:19], v[18:19], v[60:61] op_sel_hi:[1,0]
	s_waitcnt vmcnt(11)
	v_pk_mul_f32 v[16:17], v[36:37], v[16:17]
	v_pk_mul_f32 v[18:19], v[38:39], v[18:19]
	v_cvt_pk_bf16_f32 v16, v16, v17
	v_cvt_pk_bf16_f32 v17, v18, v19
	v_lshlrev_b64 v[18:19], 11, v[68:69]
	v_pk_mul_f32 v[20:21], v[20:21], v[60:61] op_sel_hi:[1,0]
	v_pk_mul_f32 v[22:23], v[22:23], v[60:61] op_sel_hi:[1,0]
	v_lshl_add_u64 v[18:19], v[62:63], 0, v[18:19]
	global_store_dwordx2 v[18:19], v[16:17], off
	v_pk_mul_f32 v[24:25], v[24:25], v[60:61] op_sel_hi:[1,0]
	v_pk_mul_f32 v[26:27], v[26:27], v[60:61] op_sel_hi:[1,0]
	v_pk_mul_f32 v[28:29], v[28:29], v[60:61] op_sel_hi:[1,0]
	v_cmp_gt_f32_e32 vcc, s24, v96
	v_pk_mul_f32 v[30:31], v[30:31], v[60:61] op_sel_hi:[1,0]
	s_waitcnt vmcnt(9)
	v_pk_mul_f32 v[16:17], v[44:45], v[20:21]
	v_pk_mul_f32 v[20:21], v[46:47], v[22:23]
	v_cvt_pk_bf16_f32 v16, v16, v17
	v_cvt_pk_bf16_f32 v17, v20, v21
	global_store_dwordx2 v[18:19], v[16:17], off offset:512
	s_waitcnt vmcnt(9)
	v_pk_mul_f32 v[16:17], v[52:53], v[24:25]
	v_pk_mul_f32 v[20:21], v[54:55], v[26:27]
	v_cvt_pk_bf16_f32 v16, v16, v17
	v_cvt_pk_bf16_f32 v17, v20, v21
	global_store_dwordx2 v[18:19], v[16:17], off offset:1024
	v_mov_b32_e32 v26, v41
	s_waitcnt vmcnt(9)
	v_pk_mul_f32 v[16:17], v[48:49], v[28:29]
	s_nop 0
	v_cvt_pk_bf16_f32 v16, v16, v17
	v_mul_f32_e32 v17, 0x4b800000, v96
	v_cndmask_b32_e32 v17, v96, v17, vcc
	v_rsq_f32_e32 v22, v17
	v_pk_mul_f32 v[20:21], v[50:51], v[30:31]
	s_waitcnt vmcnt(8)
	v_mov_b32_e32 v24, v75
	v_cvt_pk_bf16_f32 v17, v20, v21
	global_store_dwordx2 v[18:19], v[16:17], off offset:1536
	v_mul_f32_e32 v16, 0x45800000, v22
	s_waitcnt vmcnt(8)
	v_mov_b32_e32 v25, v79
	v_cndmask_b32_e32 v16, v22, v16, vcc
	v_mov_b32_e32 v22, v74
	v_mov_b32_e32 v23, v78
	v_pk_mul_f32 v[24:25], v[24:25], v[24:25]
	v_mov_b32_e32 v20, v76
	v_mov_b32_e32 v21, v80
	v_pk_fma_f32 v[22:23], v[22:23], v[22:23], v[24:25]
	v_mov_b32_e32 v24, v77
	v_mov_b32_e32 v25, v81
	v_pk_fma_f32 v[20:21], v[20:21], v[20:21], v[22:23]
	s_waitcnt vmcnt(7)
	v_mov_b32_e32 v22, v82
	v_pk_fma_f32 v[20:21], v[24:25], v[24:25], v[20:21]
	v_mov_b32_e32 v24, v83
	s_waitcnt vmcnt(6)
	v_mov_b32_e32 v25, v87
	v_mov_b32_e32 v23, v86
	v_pk_mul_f32 v[24:25], v[24:25], v[24:25]
	s_waitcnt vmcnt(5)
	v_mov_b32_e32 v27, v91
	v_pk_fma_f32 v[22:23], v[22:23], v[22:23], v[24:25]
	v_mov_b32_e32 v24, v84
	v_mov_b32_e32 v25, v88
	v_pk_fma_f32 v[22:23], v[24:25], v[24:25], v[22:23]
	v_mov_b32_e32 v24, v85
	v_mov_b32_e32 v25, v89
	v_pk_fma_f32 v[22:23], v[24:25], v[24:25], v[22:23]
	v_mov_b32_e32 v24, v40
	v_mov_b32_e32 v25, v90
	v_pk_mul_f32 v[26:27], v[26:27], v[26:27]
	s_waitcnt vmcnt(4)
	v_mov_b32_e32 v28, v57
	v_pk_fma_f32 v[24:25], v[24:25], v[24:25], v[26:27]
	v_mov_b32_e32 v26, v42
	v_mov_b32_e32 v27, v92
	v_pk_fma_f32 v[24:25], v[26:27], v[26:27], v[24:25]
	v_mov_b32_e32 v26, v43
	v_mov_b32_e32 v27, v93
	v_mov_b32_e32 v29, v33
	v_pk_fma_f32 v[24:25], v[26:27], v[26:27], v[24:25]
	v_mov_b32_e32 v26, v56
	v_mov_b32_e32 v27, v32
	v_pk_mul_f32 v[28:29], v[28:29], v[28:29]
	v_pk_mul_f32 v[12:13], v[12:13], v[16:17] op_sel_hi:[1,0]
	v_pk_fma_f32 v[26:27], v[26:27], v[26:27], v[28:29]
	v_mov_b32_e32 v28, v58
	v_mov_b32_e32 v29, v34
	v_pk_fma_f32 v[26:27], v[28:29], v[28:29], v[26:27]
	v_mov_b32_e32 v28, v59
	v_mov_b32_e32 v29, v35
	v_pk_fma_f32 v[26:27], v[28:29], v[28:29], v[26:27]
	v_mov_b32_e32 v28, v24
	v_mov_b32_e32 v29, v20
	v_mov_b32_e32 v20, v25
	v_pk_add_f32 v[20:21], v[28:29], v[20:21]
	v_mov_b32_e32 v24, v26
	v_mov_b32_e32 v25, v22
	v_pk_add_f32 v[20:21], v[20:21], v[24:25]
	v_mov_b32_e32 v22, v27
	v_pk_add_f32 v[20:21], v[20:21], v[22:23]
	v_mov_b32_e32 v23, v21
	s_nop 1
	v_permlane32_swap_b32_e32 v23, v21
	s_nop 1
	v_mov_b32_e32 v22, v20
	s_nop 1
	v_permlane32_swap_b32_e32 v22, v20
	s_nop 1
	v_pk_mul_f32 v[14:15], v[14:15], v[16:17] op_sel_hi:[1,0]
	v_pk_mul_f32 v[12:13], v[36:37], v[12:13]
	v_pk_mul_f32 v[14:15], v[38:39], v[14:15]
	v_cvt_pk_bf16_f32 v12, v12, v13
	s_waitcnt lgkmcnt(0)
	v_pk_add_f32 v[20:21], v[20:21], v[22:23]
	v_mov_b32_e32 v23, v21
	s_nop 1
	v_permlane16_swap_b32_e32 v23, v21
	s_nop 1
	v_mov_b32_e32 v22, v20
	s_nop 1
	v_permlane16_swap_b32_e32 v22, v20
	s_nop 1
	v_cvt_pk_bf16_f32 v13, v14, v15
	global_store_dwordx2 v[18:19], v[12:13], off offset:2048
	v_pk_mul_f32 v[8:9], v[8:9], v[16:17] op_sel_hi:[1,0]
	v_pk_mul_f32 v[10:11], v[10:11], v[16:17] op_sel_hi:[1,0]
	s_waitcnt lgkmcnt(0)
; DI int vb_n() { return (int)gridDim.x * 2; }
; template <int NR>
; DI void rms_rows(const float* __restrict__ xr, const float* __restrict__ g, u16* __restrict__ dst, int lane) {
;     ...
;     for (int i = 0; i < 4; ++i) ss += v[r][i].x * v[r][i].x + v[r][i].y * v[r][i].y + v[r][i].z * v[r][i].z + v[r][i].w * v[r][i].w;
;     ss = wave_sum(ss);
;     const float rr = rsqrtf(ss * (1.f / 1024.f) + 1e-6f);
; #pragma unroll
;     for (int i = 0; i < 4; ++i) {
;       uint2 o;
;       o.x = pack2(v[r][i].x * rr * gg[i].x, v[r][i].y * rr * gg[i].y);
;       o.y = pack2(v[r][i].z * rr * gg[i].z, v[r][i].w * rr * gg[i].w);
;       *(uint2*)(dst + (size_t)r * 1024 + lane * 4 + 256 * i) = o;
; DI void phase_prep(const Params& p, char* smem, int part, int vb) {
;     ...
;     for (int it0 = vb; it0 < NITEMS; it0 += vb_n()) {
;       int it = it0;
;       if (it < 1024) {
;         int row = it * 16 + wave * 4;
;         rms_rows<4>(p.x + (size_t)row * 1024, p.g_mix, (u16*)(ws + WS_XN) + (size_t)row * 1024, lane);
;         continue;
	v_pk_add_f32 v[12:13], v[20:21], v[22:23]
	s_nop 1
	v_mov_b32_dpp v15, v13 row_ror:8 row_mask:0xf bank_mask:0xf
	s_nop 0
	s_nop 1
	v_mov_b32_dpp v14, v12 row_ror:8 row_mask:0xf bank_mask:0xf
	s_nop 0
	v_pk_mul_f32 v[8:9], v[44:45], v[8:9]
	v_pk_mul_f32 v[10:11], v[46:47], v[10:11]
	v_cvt_pk_bf16_f32 v8, v8, v9
	v_cvt_pk_bf16_f32 v9, v10, v11
	s_waitcnt lgkmcnt(0)
	v_pk_add_f32 v[10:11], v[12:13], v[14:15]
	s_nop 1
	v_mov_b32_dpp v13, v11 row_ror:4 row_mask:0xf bank_mask:0xf
	s_nop 0
	s_nop 1
	v_mov_b32_dpp v12, v10 row_ror:4 row_mask:0xf bank_mask:0xf
	s_nop 0
	global_store_dwordx2 v[18:19], v[8:9], off offset:2560
	v_pk_mul_f32 v[4:5], v[4:5], v[16:17] op_sel_hi:[1,0]
	v_pk_mul_f32 v[6:7], v[6:7], v[16:17] op_sel_hi:[1,0]
	v_pk_mul_f32 v[4:5], v[52:53], v[4:5]
	s_waitcnt lgkmcnt(0)
	v_pk_add_f32 v[8:9], v[10:11], v[12:13]
	s_nop 1
	v_mov_b32_dpp v11, v9 row_ror:2 row_mask:0xf bank_mask:0xf
	s_nop 0
	s_nop 1
	v_mov_b32_dpp v10, v8 row_ror:2 row_mask:0xf bank_mask:0xf
	s_nop 0
	v_pk_mul_f32 v[6:7], v[54:55], v[6:7]
	v_cvt_pk_bf16_f32 v4, v4, v5
	v_cvt_pk_bf16_f32 v5, v6, v7
	v_pk_mul_f32 v[0:1], v[0:1], v[16:17] op_sel_hi:[1,0]
	s_waitcnt lgkmcnt(0)
	v_pk_add_f32 v[6:7], v[8:9], v[10:11]
	s_nop 1
	v_mov_b32_dpp v9, v7 row_ror:1 row_mask:0xf bank_mask:0xf
	s_nop 0
	s_nop 1
	v_mov_b32_dpp v8, v6 row_ror:1 row_mask:0xf bank_mask:0xf
	s_nop 0
	global_store_dwordx2 v[18:19], v[4:5], off offset:3072
	v_pk_mul_f32 v[0:1], v[48:49], v[0:1]
	v_pk_mul_f32 v[2:3], v[2:3], v[16:17] op_sel_hi:[1,0]
	v_cvt_pk_bf16_f32 v0, v0, v1
	s_waitcnt lgkmcnt(0)
	v_pk_add_f32 v[4:5], v[6:7], v[8:9]
	v_pk_mul_f32 v[2:3], v[50:51], v[2:3]
	v_pk_fma_f32 v[4:5], v[4:5], s[6:7], v[94:95] op_sel_hi:[1,0,0]
	s_nop 0
	v_mul_f32_e32 v1, 0x4b800000, v5
	v_cmp_gt_f32_e32 vcc, s24, v5
	s_nop 1
	v_cndmask_b32_e32 v1, v5, v1, vcc
	v_rsq_f32_e32 v5, v1
	v_cvt_pk_bf16_f32 v1, v2, v3
	global_store_dwordx2 v[18:19], v[0:1], off offset:3584
	v_mul_f32_e32 v0, 0x45800000, v5
	v_cndmask_b32_e32 v0, v5, v0, vcc
	v_pk_mul_f32 v[2:3], v[74:75], v[0:1] op_sel_hi:[1,0]
	v_pk_mul_f32 v[6:7], v[76:77], v[0:1] op_sel_hi:[1,0]
	v_pk_mul_f32 v[2:3], v[36:37], v[2:3]
	v_pk_mul_f32 v[6:7], v[38:39], v[6:7]
	v_cvt_pk_bf16_f32 v2, v2, v3
	v_cvt_pk_bf16_f32 v3, v6, v7
	v_add_co_u32_e32 v6, vcc, s23, v18
	v_pk_mul_f32 v[8:9], v[80:81], v[0:1] op_sel_hi:[1,0]
	s_nop 0
	v_addc_co_u32_e32 v7, vcc, 0, v19, vcc
	global_store_dwordx2 v[6:7], v[2:3], off
	v_pk_mul_f32 v[2:3], v[78:79], v[0:1] op_sel_hi:[1,0]
	v_pk_mul_f32 v[8:9], v[46:47], v[8:9]
	v_pk_mul_f32 v[2:3], v[44:45], v[2:3]
	v_cmp_gt_f32_e32 vcc, s24, v4
	v_cvt_pk_bf16_f32 v2, v2, v3
	v_cvt_pk_bf16_f32 v3, v8, v9
	global_store_dwordx2 v[6:7], v[2:3], off offset:512
	v_pk_mul_f32 v[2:3], v[82:83], v[0:1] op_sel_hi:[1,0]
	v_pk_mul_f32 v[8:9], v[84:85], v[0:1] op_sel_hi:[1,0]
	v_pk_mul_f32 v[2:3], v[52:53], v[2:3]
	v_pk_mul_f32 v[8:9], v[54:55], v[8:9]
	v_cvt_pk_bf16_f32 v2, v2, v3
	v_cvt_pk_bf16_f32 v3, v8, v9
	global_store_dwordx2 v[6:7], v[2:3], off offset:1024
	v_pk_mul_f32 v[2:3], v[86:87], v[0:1] op_sel_hi:[1,0]
	v_pk_mul_f32 v[0:1], v[88:89], v[0:1] op_sel_hi:[1,0]
	v_pk_mul_f32 v[2:3], v[48:49], v[2:3]
	v_pk_mul_f32 v[0:1], v[50:51], v[0:1]
	v_cvt_pk_bf16_f32 v2, v2, v3
	v_mul_f32_e32 v3, 0x4b800000, v4
	v_cndmask_b32_e32 v3, v4, v3, vcc
	v_rsq_f32_e32 v4, v3
	v_cvt_pk_bf16_f32 v3, v0, v1
	global_store_dwordx2 v[6:7], v[2:3], off offset:1536
	v_mul_f32_e32 v0, 0x45800000, v4
	v_cndmask_b32_e32 v0, v4, v0, vcc
	v_pk_mul_f32 v[2:3], v[40:41], v[0:1] op_sel_hi:[1,0]
	v_pk_mul_f32 v[4:5], v[42:43], v[0:1] op_sel_hi:[1,0]
	v_pk_mul_f32 v[2:3], v[36:37], v[2:3]
	v_pk_mul_f32 v[4:5], v[38:39], v[4:5]
	v_cvt_pk_bf16_f32 v2, v2, v3
	v_cvt_pk_bf16_f32 v3, v4, v5
	global_store_dwordx2 v[6:7], v[2:3], off offset:2048
	v_pk_mul_f32 v[2:3], v[90:91], v[0:1] op_sel_hi:[1,0]
	v_pk_mul_f32 v[4:5], v[92:93], v[0:1] op_sel_hi:[1,0]
	v_pk_mul_f32 v[2:3], v[44:45], v[2:3]
	v_pk_mul_f32 v[4:5], v[46:47], v[4:5]
	v_cvt_pk_bf16_f32 v2, v2, v3
	v_cvt_pk_bf16_f32 v3, v4, v5
	global_store_dwordx2 v[6:7], v[2:3], off offset:2560
	v_pk_mul_f32 v[2:3], v[56:57], v[0:1] op_sel_hi:[1,0]
	v_pk_mul_f32 v[4:5], v[58:59], v[0:1] op_sel_hi:[1,0]
	v_pk_mul_f32 v[2:3], v[52:53], v[2:3]
	v_pk_mul_f32 v[4:5], v[54:55], v[4:5]
	v_cvt_pk_bf16_f32 v2, v2, v3
	v_cvt_pk_bf16_f32 v3, v4, v5
	global_store_dwordx2 v[6:7], v[2:3], off offset:3072
	v_pk_mul_f32 v[2:3], v[32:33], v[0:1] op_sel_hi:[1,0]
	v_pk_mul_f32 v[0:1], v[34:35], v[0:1] op_sel_hi:[1,0]
	v_pk_mul_f32 v[2:3], v[48:49], v[2:3]
	v_pk_mul_f32 v[0:1], v[50:51], v[0:1]
	v_cvt_pk_bf16_f32 v2, v2, v3
	v_cvt_pk_bf16_f32 v3, v0, v1
	global_store_dwordx2 v[6:7], v[2:3], off offset:3584
	s_branch .LBB0_19
